# early barrier k=2 + skip final grid barrier + XCD barrier instead of cg grid.sync at first seam
# speedup vs baseline: 1.0014x; 1.0014x over previous
; #define GSYNC() do { for (int _r = 0; _r < REP_SYNC; ++_r) xcd_barrier(xbar); } while (0)
; __device__ __forceinline__ void xcd_barrier(const XcdBarrier& b) {
;     asm volatile("s_waitcnt vmcnt(0)" ::: "memory");
;     __syncthreads();
;     if (threadIdx.x == 0) {
;         unsigned* bar = b.bar;
;         __builtin_amdgcn_s_waitcnt(0);
;         unsigned nloc = b.st[0], nx = b.st[1];
;         if (nloc == 0u) { xcd_barrier_complete(bar, b.x, nloc, nx); b.st[0] = nloc; b.st[1] = nx; }
; __global__ void __launch_bounds__(NTHR, 2) fwd_kernel(Args a) {
;     ...
;             if (first_seam) { grid.sync(); first_seam = false; } else GSYNC();
.LBB0_340:
	v_readlane_b32 s0, v255, 37
	v_readlane_b32 s1, v255, 38
	s_xor_b64 s[2:3], s[0:1], -1
	s_mov_b64 s[0:1], -1
	s_and_b64 vcc, exec, s[2:3]
	s_waitcnt vmcnt(0)
	s_barrier
	s_and_saveexec_b64 s[0:1], s[78:79]
	s_cbranch_execz .LBB0_429
	v_readlane_b32 s2, v255, 32
	s_waitcnt vmcnt(0) expcnt(0) lgkmcnt(0)
	s_nop 0
	v_mov_b32_e32 v0, s2
	ds_read_b32 v3, v0
	v_readlane_b32 s2, v255, 33
	s_waitcnt lgkmcnt(0)
	v_cmp_ne_u32_e32 vcc, 0, v3
	v_mov_b32_e32 v0, s2
	ds_read_b32 v2, v0
	s_cbranch_vccnz .LBB0_393
	s_mov_b32 s6, 1
	s_branch .LBB0_381

; #define GSYNC() do { for (int _r = 0; _r < REP_SYNC; ++_r) xcd_barrier(xbar); } while (0)
; __device__ __forceinline__ void xcd_barrier(const XcdBarrier& b) {
;     asm volatile("s_waitcnt vmcnt(0)" ::: "memory");
;     __syncthreads();
;     if (threadIdx.x == 0) {
;         unsigned* bar = b.bar;
;         __builtin_amdgcn_s_waitcnt(0);
;         unsigned nloc = b.st[0], nx = b.st[1];
;         if (nloc == 0u) { xcd_barrier_complete(bar, b.x, nloc, nx); b.st[0] = nloc; b.st[1] = nx; }
; __global__ void __launch_bounds__(NTHR, 2) fwd_kernel(Args a) {
;     ...
;         GSYNC();
.LBB0_938:
	s_waitcnt vmcnt(0)
	s_waitcnt lgkmcnt(0)
	s_barrier
	s_cmp_eq_u32 s24, 3
	s_cbranch_scc1 .LBB0_989
	s_and_saveexec_b64 s[0:1], s[78:79]
	s_cbranch_execz .LBB0_40
	v_readlane_b32 s2, v255, 32
	s_waitcnt vmcnt(0) expcnt(0) lgkmcnt(0)
	s_nop 0
	v_mov_b32_e32 v0, s2
	ds_read_b32 v3, v0
	v_readlane_b32 s2, v255, 33
	s_waitcnt lgkmcnt(0)
	v_cmp_ne_u32_e32 vcc, 0, v3
	v_mov_b32_e32 v0, s2
	ds_read_b32 v2, v0
	s_cbranch_vccnz .LBB0_954
	s_mov_b32 s6, 1
	s_branch .LBB0_942
